# L0 attention start unit uses the measured speed rank of the bid%8 group instead of the group index (fast groups take the 5 MLA + 4 GQA mix), on keep_v8
# speedup vs baseline: 1.0101x; 1.0038x over previous
.LBB0_512:
	s_or_b64 exec, exec, s[2:3]
	v_readlane_b32 s2, v255, 0
	v_readlane_b32 s4, v255, 34
	s_waitcnt lgkmcnt(0)
	s_barrier
	v_mbcnt_lo_u32_b32 v2, -1, 0
	v_mbcnt_hi_u32_b32 v2, -1, v2
	v_readlane_b32 s5, v255, 35
	v_add_u32_e32 v0, s2, v2
	s_mov_b64 s[16:17], s[0:1]
	v_readfirstlane_b32 s2, v0
	s_andn2_b64 vcc, exec, s[4:5]
	s_cbranch_vccnz .LBB0_617
	s_load_dwordx4 s[12:15], s[16:17], 0x120
	s_ashr_i32 s3, s2, 6
	v_and_b32_e32 v3, 63, v2
	v_bfe_u32 v5, v2, 5, 1
	v_lshlrev_b32_e32 v3, 2, v3
	s_waitcnt lgkmcnt(0)
	s_add_u32 s18, s14, 0x10f00000
	s_addc_u32 s19, s15, 0
	s_add_u32 s40, s14, 0x19600000
	s_addc_u32 s41, s15, 0
	s_ashr_i32 s42, s2, 7
	s_lshl_b32 s43, s3, 5
	s_add_u32 s44, s14, 0xac00740
	s_addc_u32 s45, s15, 0
	s_add_u32 s46, s14, 0xac00840
	s_mulk_i32 s3, 0x1200
	s_addc_u32 s47, s15, 0
	s_add_i32 s2, s3, 0
	s_add_i32 s2, s2, 0x10000
	v_and_b32_e32 v119, 31, v2
	v_lshrrev_b32_e32 v4, 2, v2
	v_lshlrev_b32_e32 v125, 2, v5
	v_xor_b32_e32 v146, 0x80, v3
	v_mov_b32_e32 v3, s2
	s_movk_i32 s3, 0x90
	v_and_b32_e32 v118, 8, v4
	v_and_or_b32 v4, v4, 3, v125
	v_lshlrev_b32_e32 v6, 1, v2
	v_lshlrev_b32_e32 v7, 3, v2
	v_mad_u32_u24 v147, v119, s3, v3
	v_and_b32_e32 v3, 7, v2
	v_mul_u32_u24_e32 v4, 0xc0, v4
	v_and_b32_e32 v6, 32, v6
	v_and_b32_e32 v7, 24, v7
	v_lshl_add_u32 v156, v3, 4, s2
	v_bfe_u32 v2, v2, 3, 3
	s_mov_b32 s2, 0x2aaaaaab
	v_or3_b32 v127, v4, v6, v7
	v_mul_u32_u24_e32 v4, 0x90, v119
	v_mul_u32_u24_e32 v157, 0x90, v2
	v_lshlrev_b32_e32 v124, 10, v2
	v_mul_hi_i32 v2, v0, s2
	v_lshl_add_u32 v129, v5, 4, v4
	v_ashrrev_i32_e32 v4, 31, v0
	v_lshlrev_b32_e32 v122, 3, v3
	v_lshrrev_b32_e32 v3, 31, v2
	v_ashrrev_i32_e32 v2, 1, v2
	v_lshrrev_b32_e32 v4, 29, v4
	v_add_u32_e32 v159, v2, v3
	v_add_u32_e32 v4, v0, v4
	s_movk_i32 s3, 0xd0
	v_mul_lo_u32 v3, v159, 12
	v_ashrrev_i32_e32 v131, 3, v4
	v_and_b32_e32 v4, 0x1ffffff8, v4
	v_mul_lo_u32 v2, v159, s3
	v_sub_u32_e32 v3, v0, v3
	v_sub_u32_e32 v4, v0, v4
	v_lshl_add_u32 v160, v3, 4, v2
	v_add_u32_e32 v2, 0x200, v0
	v_lshlrev_b32_e32 v5, 4, v0
	v_lshlrev_b32_e32 v120, 3, v4
	v_mul_hi_i32 v4, v2, s2
	v_lshl_add_u32 v145, v131, 6, v5
	v_lshrrev_b32_e32 v5, 31, v4
	v_ashrrev_i32_e32 v4, 1, v4
	v_add_u32_e32 v161, v4, v5
	v_mul_lo_u32 v5, v161, 12
	v_sub_u32_e32 v2, v2, v5
	v_mul_lo_u32 v4, v161, s3
	s_movk_i32 s2, 0x300
	v_lshlrev_b32_e32 v132, 3, v3
	s_movk_i32 s4, 0x100
	v_lshlrev_b32_e32 v134, 3, v2
	v_and_or_b32 v123, s43, 32, v119
	v_add_lshl_u32 v144, v131, v0, 4
	v_ashrrev_i32_e32 v121, 31, v120
	v_or_b32_e32 v126, 0x2000, v124
	v_or_b32_e32 v128, 0x4000, v124
	v_or_b32_e32 v130, 0x6000, v124
	v_lshl_add_u32 v158, v119, 6, v129
	v_lshl_add_u32 v162, v2, 4, v4
	v_cmp_gt_i32_e64 s[2:3], s2, v0
	v_ashrrev_i32_e32 v133, 31, v132
	v_cmp_gt_i32_e64 s[4:5], s4, v0
	v_ashrrev_i32_e32 v135, 31, v134
	v_readlane_b32 s48, v255, 51
	v_readlane_b32 s49, v255, 50
	s_nop 3
	s_cmpk_lg_u32 s33, 0x100
	s_cbranch_scc1 .La0_done
	s_load_dwordx2 s[98:99], s[0:1], 0x128
	s_and_b32 s101, s8, 7
	s_lshl_b32 s101, s101, 8
	s_waitcnt lgkmcnt(0)
	s_add_u32 s98, s98, s101
	s_addc_u32 s99, s99, 0
	s_add_u32 s98, s98, 0x302400
	s_addc_u32 s99, s99, 0
	global_load_dword v253, v1, s[98:99] sc1
	s_waitcnt vmcnt(0)
	v_readfirstlane_b32 s101, v253
	s_nop 3
	s_and_b32 s101, s101, 7
	s_lshl_b32 s101, s101, 5
	s_lshr_b32 s100, s8, 3
	s_add_i32 s100, s100, s101
	s_sub_i32 s101, s100, s49
	s_mov_b32 s49, s100
	s_add_i32 s48, s48, s101
.La0_done:
	s_branch .LBB0_516
.LBB0_514:
	ds_bpermute_b32 v34, v146, v0
	s_ashr_i32 s23, s22, 31
	s_lshl_b64 s[6:7], s[22:23], 11
	s_add_u32 s9, s12, s6
	s_addc_u32 s20, s13, s7
	s_waitcnt lgkmcnt(0)
	v_add_f32_e32 v0, v0, v34
	v_div_scale_f32 v34, s[6:7], v0, v0, 1.0
	v_rcp_f32_e32 v35, v34
	s_waitcnt lgkmcnt(0)
	s_barrier
	v_fma_f32 v36, -v34, v35, 1.0
	v_fmac_f32_e32 v35, v36, v35
	v_div_scale_f32 v36, vcc, 1.0, v0, 1.0
	v_mul_f32_e32 v37, v36, v35
	v_fma_f32 v38, -v34, v37, v36
	v_fmac_f32_e32 v37, v38, v35
	v_fma_f32 v34, -v34, v37, v36
	v_div_fmas_f32 v34, v34, v35, v37
	v_div_fixup_f32 v0, v34, v0, 1.0
	v_pk_mul_f32 v[18:19], v[18:19], v[0:1] op_sel_hi:[1,0]
	v_pk_mul_f32 v[20:21], v[20:21], v[0:1] op_sel_hi:[1,0]
	v_pk_mul_f32 v[2:3], v[2:3], v[0:1] op_sel_hi:[1,0]
	v_pk_mul_f32 v[4:5], v[4:5], v[0:1] op_sel_hi:[1,0]
	v_cvt_pk_bf16_f32 v18, v18, v19
	v_cvt_pk_bf16_f32 v19, v20, v21
	v_pk_mul_f32 v[20:21], v[22:23], v[0:1] op_sel_hi:[1,0]
	v_pk_mul_f32 v[22:23], v[24:25], v[0:1] op_sel_hi:[1,0]
	v_cvt_pk_bf16_f32 v2, v2, v3
	v_cvt_pk_bf16_f32 v3, v4, v5
	v_pk_mul_f32 v[4:5], v[6:7], v[0:1] op_sel_hi:[1,0]
	v_pk_mul_f32 v[6:7], v[8:9], v[0:1] op_sel_hi:[1,0]
	v_add_u32_e32 v34, v147, v118
	v_cvt_pk_bf16_f32 v20, v20, v21
	v_cvt_pk_bf16_f32 v21, v22, v23
	v_cvt_pk_bf16_f32 v4, v4, v5
	v_cvt_pk_bf16_f32 v5, v6, v7
	ds_write2_b64 v34, v[18:19], v[20:21] offset1:2
	v_pk_mul_f32 v[18:19], v[26:27], v[0:1] op_sel_hi:[1,0]
	v_pk_mul_f32 v[20:21], v[28:29], v[0:1] op_sel_hi:[1,0]
	ds_write2_b64 v34, v[2:3], v[4:5] offset0:8 offset1:10
	v_pk_mul_f32 v[2:3], v[10:11], v[0:1] op_sel_hi:[1,0]
	v_pk_mul_f32 v[4:5], v[12:13], v[0:1] op_sel_hi:[1,0]
	v_cvt_pk_bf16_f32 v18, v18, v19
	v_cvt_pk_bf16_f32 v19, v20, v21
	v_pk_mul_f32 v[20:21], v[30:31], v[0:1] op_sel_hi:[1,0]
	v_pk_mul_f32 v[22:23], v[32:33], v[0:1] op_sel_hi:[1,0]
	v_cvt_pk_bf16_f32 v2, v2, v3
	v_cvt_pk_bf16_f32 v3, v4, v5
	v_pk_mul_f32 v[4:5], v[14:15], v[0:1] op_sel_hi:[1,0]
	v_pk_mul_f32 v[6:7], v[16:17], v[0:1] op_sel_hi:[1,0]
	v_cvt_pk_bf16_f32 v20, v20, v21
	v_cvt_pk_bf16_f32 v21, v22, v23
	v_cvt_pk_bf16_f32 v4, v4, v5
	v_cvt_pk_bf16_f32 v5, v6, v7
	ds_write2_b64 v34, v[18:19], v[20:21] offset0:4 offset1:6
	ds_write2_b64 v34, v[2:3], v[4:5] offset0:12 offset1:14
	s_waitcnt lgkmcnt(0)
	v_add_u32_e32 v14, v156, v157
	s_lshl_b32 s6, s29, 7
	ds_read_b128 v[2:5], v14
	ds_read_b128 v[6:9], v14 offset:1152
	s_add_u32 s6, s9, s6
	s_addc_u32 s7, s20, 0
	v_lshlrev_b32_e32 v0, 1, v122
	v_lshl_add_u64 v[10:11], s[6:7], 0, v[0:1]
	v_lshlrev_b32_e32 v0, 1, v124
	v_lshl_add_u64 v[12:13], v[10:11], 0, v[0:1]
	v_lshlrev_b32_e32 v0, 1, v126
	s_waitcnt lgkmcnt(1)
	global_store_dwordx4 v[12:13], v[2:5], off
	v_lshl_add_u64 v[12:13], v[10:11], 0, v[0:1]
	ds_read_b128 v[2:5], v14 offset:2304
	s_waitcnt lgkmcnt(1)
	global_store_dwordx4 v[12:13], v[6:9], off
	ds_read_b128 v[6:9], v14 offset:3456
	v_lshlrev_b32_e32 v0, 1, v128
	v_lshl_add_u64 v[12:13], v[10:11], 0, v[0:1]
	v_lshlrev_b32_e32 v0, 1, v130
	s_waitcnt lgkmcnt(1)
	global_store_dwordx4 v[12:13], v[2:5], off
	s_nop 1
	v_lshl_add_u64 v[2:3], v[10:11], 0, v[0:1]
	s_waitcnt lgkmcnt(0)
	global_store_dwordx4 v[2:3], v[6:9], off
	s_waitcnt lgkmcnt(0)
